# scan chunk loop: waves 4-7 issue their next-chunk loads after their first MFMA block (memory pipe alternates between the wave halves)
# speedup vs baseline: 1.0585x; 1.0038x over previous
; #define LAS __attribute__((address_space(3)))
; __device__ __forceinline__ void scan_phase(const Params& p, int bid, int nblk, LAS unsigned char* lds) {
;     ...
;         auto gload = [&](int n) {
;             const size_t it = (size_t)(bh * 32 + n);
; #pragma unroll
;             for (int i = 0; i < 2; ++i) { const int ch = tid + 512 * i; r_wd[i] = *(const u32x4*)(wdc + it * 8192 + ch * 8); r_qd[i] = *(const u32x4*)(qd + it * 8192 + ch * 8); r_kt[i] = *(const u32x4*)(kt + it * 8192 + ch * 8); }
;             r_qk = *(const u32x4*)(qk + it * 4096 + tid * 8);
;             if (tid < 256) r_ub = *(const u32x4*)(ub + it * 8192 + (tid >> 2) * 128 + sl * 16 + (tid & 3) * 4);
;     ...
;         for (int n = 0; n < 32; ++n) {
;             const int cur = n & 1; LAS unsigned char* B = lds + cur * SB_SIZE;
;             if (n + 1 < 32) gload(n + 1);
;             const float cd = __builtin_bit_cast(float, __builtin_amdgcn_readlane(__builtin_bit_cast(int, cdall), n));
.LBB0_1080:
	s_cmp_lg_u32 s35, 0
	s_cbranch_scc1 .Lscan_nw
	s_waitcnt vmcnt(0)
.Lscan_nw:
	s_and_b64 vcc, exec, s[18:19]
	s_cbranch_vccnz .Lscan_skipld
	v_lshl_add_u64 v[24:25], s[26:27], 0, v[48:49]
	v_add_co_u32_e32 v16, vcc, 0xe53d000, v24
	v_lshl_add_u64 v[32:33], s[28:29], 0, v[48:49]
	s_nop 0
	v_addc_co_u32_e32 v17, vcc, 0, v25, vcc
	v_add_co_u32_e32 v18, vcc, 0xf53d000, v24
	s_nop 1
	v_addc_co_u32_e32 v19, vcc, 0, v25, vcc
	global_load_dwordx4 v[8:11], v[16:17], off
	global_load_dwordx4 v[12:15], v[18:19], off
	v_add_co_u32_e32 v16, vcc, 0x1053d000, v24
	s_nop 1
	v_addc_co_u32_e32 v17, vcc, 0, v25, vcc
	v_add_co_u32_e32 v20, vcc, 0xe53f000, v24
	s_nop 1
	v_addc_co_u32_e32 v21, vcc, 0, v25, vcc
	v_add_co_u32_e32 v26, vcc, 0xf53f000, v24
	global_load_dwordx4 v[16:19], v[16:17], off
	s_nop 0
	global_load_dwordx4 v[20:23], v[20:21], off
	v_addc_co_u32_e32 v27, vcc, 0, v25, vcc
	v_add_co_u32_e32 v28, vcc, 0x1053f000, v24
	s_nop 1
	v_addc_co_u32_e32 v29, vcc, 0, v25, vcc
	global_load_dwordx4 v[24:27], v[26:27], off
	s_nop 0
	global_load_dwordx4 v[28:31], v[28:29], off
	s_nop 0
	global_load_dwordx4 v[32:35], v[32:33], off
	s_and_saveexec_b64 s[8:9], s[6:7]
	s_cbranch_execz .LBB0_1082
	global_load_dwordx4 v[0:3], v[72:73], off

; #define LAS __attribute__((address_space(3)))
; __device__ __forceinline__ unsigned pk2(float lo, float hi) { const f32x2 v = {lo, hi}; const bf16x2_hw b = __builtin_convertvector(v, bf16x2_hw); return __builtin_bit_cast(unsigned, b); }
; __device__ __forceinline__ void scan_phase(const Params& p, int bid, int nblk, LAS unsigned char* lds) {
;     ...
;         auto gload = [&](int n) {
;             const size_t it = (size_t)(bh * 32 + n);
; #pragma unroll
;             for (int i = 0; i < 2; ++i) { const int ch = tid + 512 * i; r_wd[i] = *(const u32x4*)(wdc + it * 8192 + ch * 8); r_qd[i] = *(const u32x4*)(qd + it * 8192 + ch * 8); r_kt[i] = *(const u32x4*)(kt + it * 8192 + ch * 8); }
;             r_qk = *(const u32x4*)(qk + it * 4096 + tid * 8);
;     ...
;             const float cd = __builtin_bit_cast(float, __builtin_amdgcn_readlane(__builtin_bit_cast(int, cdall), n));
;             f32x4 acc;
;             const int tw = wid & 3;
;             if (wid < 4) {
; #pragma unroll
;                 for (int j = 0; j < 4; ++j) acc[j] = *(const LAS float*)(B + SB_UB + ((tw * 16 + fq * 4 + j) * 16 + fr) * 4);
; #pragma unroll
;                 for (int kk = 0; kk < 4; ++kk) { const bf16x8 a = *(const LAS bf16x8*)(B + SB_WD + (tw * 16 + fr) * 272 + (kk * 32 + fq * 8) * 2); const bf16x8 bb = *(const LAS bf16x8*)(lds + SC_ST + fr * 272 + (kk * 32 + fq * 8) * 2);
;                     acc = __builtin_amdgcn_mfma_f32_16x16x32_bf16(a, bb, acc, 0, 0, 0); }
;                 u32x2 w; w.x = pk2(acc[0], acc[1]); w.y = pk2(acc[2], acc[3]);
;                 *(LAS u32x2*)(lds + SC_UT + fr * 144 + (tw * 16 + fq * 4) * 2) = w;
;             } else {
;                 acc = (f32x4){0.f, 0.f, 0.f, 0.f};
; #pragma unroll
;                 for (int kk = 0; kk < 4; ++kk) { const bf16x8 a = *(const LAS bf16x8*)(B + SB_QD + (tw * 16 + fr) * 272 + (kk * 32 + fq * 8) * 2); const bf16x8 bb = *(const LAS bf16x8*)(lds + SC_ST + fr * 272 + (kk * 32 + fq * 8) * 2);
;                     acc = __builtin_amdgcn_mfma_f32_16x16x32_bf16(a, bb, acc, 0, 0, 0); }
.Lscan_skipld:
	s_and_b32 s42, s35, 1
	s_mul_i32 s8, s42, 0x10400
	v_cndmask_b32_e64 v36, 0, 1, s[18:19]
	s_add_i32 s43, s8, 0
	v_readlane_b32 s16, v69, s35
	v_cmp_ne_u32_e64 s[8:9], 1, v36
	s_andn2_b64 vcc, exec, s[18:19]
	s_mov_b64 s[30:31], -1
	s_cbranch_vccnz .LBB0_1084
	v_add3_u32 v112, s43, v90, v84
	ds_read_b128 v[36:39], v112 offset:17408
	v_add_u32_e32 v116, v86, v84
	ds_read_b128 v[40:43], v112 offset:17472
	ds_read_b128 v[44:47], v116
	ds_read_b128 v[108:111], v116 offset:64
	s_mov_b64 s[30:31], 0
	s_waitcnt lgkmcnt(1)
	v_mfma_f32_16x16x32_bf16 v[36:39], v[36:39], v[44:47], 0
	ds_read_b128 v[44:47], v112 offset:17536
	ds_read_b128 v[112:115], v112 offset:17600
	s_waitcnt lgkmcnt(2)
	v_mfma_f32_16x16x32_bf16 v[36:39], v[40:43], v[108:111], v[36:39]
	ds_read_b128 v[40:43], v116 offset:128
	ds_read_b128 v[108:111], v116 offset:192
	s_waitcnt lgkmcnt(1)
	v_mfma_f32_16x16x32_bf16 v[36:39], v[44:47], v[40:43], v[36:39]
	s_waitcnt lgkmcnt(0)
	v_mfma_f32_16x16x32_bf16 v[36:39], v[112:115], v[108:111], v[36:39]
	v_lshl_add_u64 v[24:25], s[26:27], 0, v[48:49]
	v_add_co_u32_e32 v16, vcc, 0xe53d000, v24
	v_lshl_add_u64 v[32:33], s[28:29], 0, v[48:49]
	s_nop 0
	v_addc_co_u32_e32 v17, vcc, 0, v25, vcc
	v_add_co_u32_e32 v18, vcc, 0xf53d000, v24
	s_nop 1
	v_addc_co_u32_e32 v19, vcc, 0, v25, vcc
	global_load_dwordx4 v[8:11], v[16:17], off
	global_load_dwordx4 v[12:15], v[18:19], off
	v_add_co_u32_e32 v16, vcc, 0x1053d000, v24
	s_nop 1
	v_addc_co_u32_e32 v17, vcc, 0, v25, vcc
	v_add_co_u32_e32 v20, vcc, 0xe53f000, v24
	s_nop 1
	v_addc_co_u32_e32 v21, vcc, 0, v25, vcc
	v_add_co_u32_e32 v26, vcc, 0xf53f000, v24
	global_load_dwordx4 v[16:19], v[16:17], off
	s_nop 0
	global_load_dwordx4 v[20:23], v[20:21], off
	v_addc_co_u32_e32 v27, vcc, 0, v25, vcc
	v_add_co_u32_e32 v28, vcc, 0x1053f000, v24
	s_nop 1
	v_addc_co_u32_e32 v29, vcc, 0, v25, vcc
	global_load_dwordx4 v[24:27], v[26:27], off
	s_nop 0
	global_load_dwordx4 v[28:31], v[28:29], off
	s_nop 0
	global_load_dwordx4 v[32:35], v[32:33], off
